# fc2 fused epilogue: half-waves trade 16-byte pieces (v_permlane32_swap) so each out store writes 64 contiguous bytes per row
# speedup vs baseline: 1.0088x; 1.0035x over previous
.LBB0_100:
	s_add_u32 s21, s48, 0xfff00080
	s_addc_u32 s28, s49, -1
	s_add_i32 s60, 0, 0x10000
	v_add_u32_e32 v124, s60, v175
	ds_read_b128 v[112:115], v124
	ds_read_b128 v[116:119], v124 offset:1024
	ds_read_b128 v[120:123], v124 offset:2048
	ds_read_b128 v[124:127], v124 offset:3072
	s_cmp_eq_u32 s20, 60
	s_cselect_b32 s51, s43, s28
	s_cselect_b32 s50, s24, s21
	s_cselect_b32 s29, s1, vcc_hi
	s_cselect_b32 s28, s25, vcc_lo
	s_add_i32 m0, s55, 0xc000
	ds_read_b128 v[128:131], v199
	ds_read_b128 v[132:135], v199 offset:1024
	ds_read_b128 v[162:165], v199 offset:2048
	ds_read_b128 v[166:169], v199 offset:3072
	ds_read_b128 v[170:173], v199 offset:4096
	ds_read_b128 v[200:203], v199 offset:5120
	ds_read_b128 v[204:207], v199 offset:6144
	ds_read_b128 v[208:211], v199 offset:7168
	global_load_lds_dwordx4 v158, s[48:49]
	s_add_i32 m0, s55, 0xe000
	s_nop 0
	global_load_lds_dwordx4 v160, s[48:49]
	s_waitcnt lgkmcnt(8)
	s_barrier
	s_waitcnt lgkmcnt(0)
	v_mfma_f32_16x16x32_bf16 v[148:151], v[112:115], v[128:131], v[148:151]
	v_mfma_f32_16x16x32_bf16 v[144:147], v[120:123], v[128:131], v[144:147]
	v_mfma_f32_16x16x32_bf16 v[108:111], v[112:115], v[162:165], v[108:111]
	v_mfma_f32_16x16x32_bf16 v[104:107], v[120:123], v[162:165], v[104:107]
	v_mfma_f32_16x16x32_bf16 v[92:95], v[112:115], v[170:173], v[92:95]
	v_mfma_f32_16x16x32_bf16 v[88:91], v[120:123], v[170:173], v[88:91]
	v_mfma_f32_16x16x32_bf16 v[76:79], v[112:115], v[204:207], v[76:79]
	v_mfma_f32_16x16x32_bf16 v[72:75], v[120:123], v[204:207], v[72:75]
	v_mfma_f32_16x16x32_bf16 v[148:151], v[116:119], v[132:135], v[148:151]
	v_mfma_f32_16x16x32_bf16 v[144:147], v[124:127], v[132:135], v[144:147]
	v_mfma_f32_16x16x32_bf16 v[108:111], v[116:119], v[166:169], v[108:111]
	v_mfma_f32_16x16x32_bf16 v[104:107], v[124:127], v[166:169], v[104:107]
	v_mfma_f32_16x16x32_bf16 v[92:95], v[116:119], v[200:203], v[92:95]
	v_mfma_f32_16x16x32_bf16 v[88:91], v[124:127], v[200:203], v[88:91]
	v_mfma_f32_16x16x32_bf16 v[76:79], v[116:119], v[208:211], v[76:79]
	v_mfma_f32_16x16x32_bf16 v[72:75], v[124:127], v[208:211], v[72:75]
	s_barrier
	s_add_i32 s21, 0, 0x14000
	v_add_u32_e32 v184, s21, v175
	s_add_i32 s60, s60, s54
	ds_read_b128 v[212:215], v184
	ds_read_b128 v[216:219], v184 offset:1024
	ds_read_b128 v[232:235], v184 offset:2048
	ds_read_b128 v[236:239], v184 offset:3072
	s_add_u32 s72, s28, s52
	s_addc_u32 s73, s29, s53
	s_mov_b32 m0, s60
	s_nop 0
	global_load_lds_dwordx4 v176, s[28:29]
	s_add_i32 m0, s60, 0x2000
	s_nop 0
	global_load_lds_dwordx4 v152, s[28:29]
	s_barrier
	s_waitcnt lgkmcnt(0)
	v_mfma_f32_16x16x32_bf16 v[140:143], v[212:215], v[128:131], v[140:143]
	v_mfma_f32_16x16x32_bf16 v[100:103], v[212:215], v[162:165], v[100:103]
	v_mfma_f32_16x16x32_bf16 v[96:99], v[232:235], v[162:165], v[96:99]
	v_mfma_f32_16x16x32_bf16 v[84:87], v[212:215], v[170:173], v[84:87]
	v_mfma_f32_16x16x32_bf16 v[80:83], v[232:235], v[170:173], v[80:83]
	v_mfma_f32_16x16x32_bf16 v[68:71], v[212:215], v[204:207], v[68:71]
	v_mfma_f32_16x16x32_bf16 v[64:67], v[232:235], v[204:207], v[64:67]
	v_mfma_f32_16x16x32_bf16 v[140:143], v[216:219], v[132:135], v[140:143]
	v_mfma_f32_16x16x32_bf16 v[128:131], v[232:235], v[128:131], v[136:139]
	v_mfma_f32_16x16x32_bf16 v[100:103], v[216:219], v[166:169], v[100:103]
	v_mfma_f32_16x16x32_bf16 v[96:99], v[236:239], v[166:169], v[96:99]
	v_mfma_f32_16x16x32_bf16 v[84:87], v[216:219], v[200:203], v[84:87]
	v_mfma_f32_16x16x32_bf16 v[80:83], v[236:239], v[200:203], v[80:83]
	v_mfma_f32_16x16x32_bf16 v[68:71], v[216:219], v[208:211], v[68:71]
	v_mfma_f32_16x16x32_bf16 v[64:67], v[236:239], v[208:211], v[64:67]
	v_mfma_f32_16x16x32_bf16 v[128:131], v[236:239], v[132:135], v[128:131]
	s_mov_b32 m0, s55
	s_add_u32 s94, s50, s52
	s_addc_u32 s95, s51, s53
	s_barrier
	ds_read_b128 v[132:135], v199 offset:16384
	ds_read_b128 v[136:139], v199 offset:17408
	ds_read_b128 v[162:165], v199 offset:18432
	ds_read_b128 v[166:169], v199 offset:19456
	ds_read_b128 v[170:173], v199 offset:20480
	ds_read_b128 v[200:203], v199 offset:21504
	ds_read_b128 v[204:207], v199 offset:22528
	ds_read_b128 v[208:211], v199 offset:23552
	global_load_lds_dwordx4 v156, s[50:51]
	s_mov_b32 m0, s56
	s_nop 0
	global_load_lds_dwordx4 v154, s[50:51]
	s_barrier
	s_waitcnt lgkmcnt(0)
	v_mfma_f32_16x16x32_bf16 v[60:63], v[112:115], v[132:135], v[60:63]
	v_mfma_f32_16x16x32_bf16 v[56:59], v[120:123], v[132:135], v[56:59]
	v_mfma_f32_16x16x32_bf16 v[44:47], v[112:115], v[162:165], v[44:47]
	v_mfma_f32_16x16x32_bf16 v[40:43], v[120:123], v[162:165], v[40:43]
	v_mfma_f32_16x16x32_bf16 v[28:31], v[112:115], v[170:173], v[28:31]
	v_mfma_f32_16x16x32_bf16 v[24:27], v[120:123], v[170:173], v[24:27]
	v_mfma_f32_16x16x32_bf16 v[12:15], v[112:115], v[204:207], v[12:15]
	v_mfma_f32_16x16x32_bf16 v[8:11], v[120:123], v[204:207], v[8:11]
	v_mfma_f32_16x16x32_bf16 v[60:63], v[116:119], v[136:139], v[60:63]
	v_mfma_f32_16x16x32_bf16 v[56:59], v[124:127], v[136:139], v[56:59]
	v_mfma_f32_16x16x32_bf16 v[44:47], v[116:119], v[166:169], v[44:47]
	v_mfma_f32_16x16x32_bf16 v[40:43], v[124:127], v[166:169], v[40:43]
	v_mfma_f32_16x16x32_bf16 v[28:31], v[116:119], v[200:203], v[28:31]
	v_mfma_f32_16x16x32_bf16 v[24:27], v[124:127], v[200:203], v[24:27]
	v_mfma_f32_16x16x32_bf16 v[12:15], v[116:119], v[208:211], v[12:15]
	v_mfma_f32_16x16x32_bf16 v[8:11], v[124:127], v[208:211], v[8:11]
	s_barrier
	s_add_u32 s60, s28, 0x100000
	s_addc_u32 s61, s29, 0
	s_add_i32 s21, s21, s54
	s_mov_b32 m0, s21
	s_nop 0
	global_load_lds_dwordx4 v176, s[60:61]
	s_add_i32 m0, s21, 0x2000
	s_nop 0
	global_load_lds_dwordx4 v152, s[60:61]
	s_waitcnt vmcnt(6)
	s_barrier
	v_mfma_f32_16x16x32_bf16 v[52:55], v[212:215], v[132:135], v[52:55]
	v_mfma_f32_16x16x32_bf16 v[48:51], v[232:235], v[132:135], v[48:51]
	v_mfma_f32_16x16x32_bf16 v[36:39], v[212:215], v[162:165], v[36:39]
	v_mfma_f32_16x16x32_bf16 v[32:35], v[232:235], v[162:165], v[32:35]
	v_mfma_f32_16x16x32_bf16 v[20:23], v[212:215], v[170:173], v[20:23]
	v_mfma_f32_16x16x32_bf16 v[16:19], v[232:235], v[170:173], v[16:19]
	v_mfma_f32_16x16x32_bf16 v[4:7], v[212:215], v[204:207], v[4:7]
	v_mfma_f32_16x16x32_bf16 v[0:3], v[232:235], v[204:207], v[0:3]
	v_mfma_f32_16x16x32_bf16 v[52:55], v[216:219], v[136:139], v[52:55]
	v_mfma_f32_16x16x32_bf16 v[48:51], v[236:239], v[136:139], v[48:51]
	v_mfma_f32_16x16x32_bf16 v[36:39], v[216:219], v[166:169], v[36:39]
	v_mfma_f32_16x16x32_bf16 v[32:35], v[236:239], v[166:169], v[32:35]
	v_mfma_f32_16x16x32_bf16 v[20:23], v[216:219], v[200:203], v[20:23]
	v_mfma_f32_16x16x32_bf16 v[16:19], v[236:239], v[200:203], v[16:19]
	v_mfma_f32_16x16x32_bf16 v[4:7], v[216:219], v[208:211], v[4:7]
	v_mfma_f32_16x16x32_bf16 v[0:3], v[236:239], v[208:211], v[0:3]
	s_add_i32 s21, 0, 0x18000
	v_add_u32_e32 v124, s21, v175
	s_barrier
	ds_read_b128 v[112:115], v124
	ds_read_b128 v[116:119], v124 offset:1024
	ds_read_b128 v[120:123], v124 offset:2048
	ds_read_b128 v[124:127], v124 offset:3072
	s_add_u32 s50, s50, 0x100000
	s_addc_u32 s51, s51, 0
	s_mov_b32 m0, s57
	ds_read_b128 v[132:135], v199 offset:32768
	ds_read_b128 v[136:139], v199 offset:33792
	ds_read_b128 v[162:165], v199 offset:34816
	ds_read_b128 v[166:169], v199 offset:35840
	ds_read_b128 v[170:173], v199 offset:36864
	ds_read_b128 v[200:203], v199 offset:37888
	ds_read_b128 v[204:207], v199 offset:38912
	ds_read_b128 v[208:211], v199 offset:39936
	global_load_lds_dwordx4 v156, s[50:51]
	s_mov_b32 m0, s58
	s_nop 0
	global_load_lds_dwordx4 v154, s[50:51]
	s_waitcnt lgkmcnt(8)
	s_barrier
	s_waitcnt lgkmcnt(0)
	v_mfma_f32_16x16x32_bf16 v[148:151], v[112:115], v[132:135], v[148:151]
	v_mfma_f32_16x16x32_bf16 v[144:147], v[120:123], v[132:135], v[144:147]
	v_mfma_f32_16x16x32_bf16 v[108:111], v[112:115], v[162:165], v[108:111]
	v_mfma_f32_16x16x32_bf16 v[104:107], v[120:123], v[162:165], v[104:107]
	v_mfma_f32_16x16x32_bf16 v[92:95], v[112:115], v[170:173], v[92:95]
	v_mfma_f32_16x16x32_bf16 v[88:91], v[120:123], v[170:173], v[88:91]
	v_mfma_f32_16x16x32_bf16 v[76:79], v[112:115], v[204:207], v[76:79]
	v_mfma_f32_16x16x32_bf16 v[72:75], v[120:123], v[204:207], v[72:75]
	v_mfma_f32_16x16x32_bf16 v[148:151], v[116:119], v[136:139], v[148:151]
	v_mfma_f32_16x16x32_bf16 v[144:147], v[124:127], v[136:139], v[144:147]
	v_mfma_f32_16x16x32_bf16 v[108:111], v[116:119], v[166:169], v[108:111]
	v_mfma_f32_16x16x32_bf16 v[104:107], v[124:127], v[166:169], v[104:107]
	v_mfma_f32_16x16x32_bf16 v[92:95], v[116:119], v[200:203], v[92:95]
	v_mfma_f32_16x16x32_bf16 v[88:91], v[124:127], v[200:203], v[88:91]
	v_mfma_f32_16x16x32_bf16 v[76:79], v[116:119], v[208:211], v[76:79]
	v_mfma_f32_16x16x32_bf16 v[72:75], v[124:127], v[208:211], v[72:75]
	s_barrier
	s_add_i32 s50, 0, 0x1c000
	s_add_i32 s21, s21, s54
	v_add_u32_e32 v231, s50, v175
	s_mov_b32 m0, s21
	ds_read_b128 v[212:215], v231
	ds_read_b128 v[216:219], v231 offset:1024
	ds_read_b128 v[232:235], v231 offset:2048
	ds_read_b128 v[236:239], v231 offset:3072
	global_load_lds_dwordx4 v176, s[72:73]
	s_add_i32 m0, s21, 0x2000
	s_nop 0
	global_load_lds_dwordx4 v152, s[72:73]
	s_barrier
	s_waitcnt lgkmcnt(0)
	v_mfma_f32_16x16x32_bf16 v[140:143], v[212:215], v[132:135], v[140:143]
	v_mfma_f32_16x16x32_bf16 v[128:131], v[232:235], v[132:135], v[128:131]
	v_mfma_f32_16x16x32_bf16 v[100:103], v[212:215], v[162:165], v[100:103]
	v_mfma_f32_16x16x32_bf16 v[96:99], v[232:235], v[162:165], v[96:99]
	v_mfma_f32_16x16x32_bf16 v[84:87], v[212:215], v[170:173], v[84:87]
	v_mfma_f32_16x16x32_bf16 v[80:83], v[232:235], v[170:173], v[80:83]
	v_mfma_f32_16x16x32_bf16 v[68:71], v[212:215], v[204:207], v[68:71]
	v_mfma_f32_16x16x32_bf16 v[64:67], v[232:235], v[204:207], v[64:67]
	v_mfma_f32_16x16x32_bf16 v[140:143], v[216:219], v[136:139], v[140:143]
	v_mfma_f32_16x16x32_bf16 v[136:139], v[236:239], v[136:139], v[128:131]
	v_mfma_f32_16x16x32_bf16 v[100:103], v[216:219], v[166:169], v[100:103]
	v_mfma_f32_16x16x32_bf16 v[96:99], v[236:239], v[166:169], v[96:99]
	v_mfma_f32_16x16x32_bf16 v[84:87], v[216:219], v[200:203], v[84:87]
	v_mfma_f32_16x16x32_bf16 v[80:83], v[236:239], v[200:203], v[80:83]
	v_mfma_f32_16x16x32_bf16 v[68:71], v[216:219], v[208:211], v[68:71]
	v_mfma_f32_16x16x32_bf16 v[64:67], v[236:239], v[208:211], v[64:67]
	s_mov_b32 m0, s7
	s_barrier
	ds_read_b128 v[128:131], v199 offset:49152
	ds_read_b128 v[132:135], v199 offset:50176
	ds_read_b128 v[162:165], v199 offset:51200
	ds_read_b128 v[166:169], v199 offset:52224
	ds_read_b128 v[170:173], v199 offset:53248
	ds_read_b128 v[200:203], v199 offset:54272
	ds_read_b128 v[204:207], v199 offset:55296
	ds_read_b128 v[208:211], v199 offset:56320
	global_load_lds_dwordx4 v156, s[94:95]
	s_mov_b32 m0, s15
	s_nop 0
	global_load_lds_dwordx4 v154, s[94:95]
	s_barrier
	s_waitcnt lgkmcnt(0)
	v_mfma_f32_16x16x32_bf16 v[60:63], v[112:115], v[128:131], v[60:63]
	v_mfma_f32_16x16x32_bf16 v[56:59], v[120:123], v[128:131], v[56:59]
	v_mfma_f32_16x16x32_bf16 v[44:47], v[112:115], v[162:165], v[44:47]
	v_mfma_f32_16x16x32_bf16 v[40:43], v[120:123], v[162:165], v[40:43]
	v_mfma_f32_16x16x32_bf16 v[28:31], v[112:115], v[170:173], v[28:31]
	v_mfma_f32_16x16x32_bf16 v[24:27], v[120:123], v[170:173], v[24:27]
	v_mfma_f32_16x16x32_bf16 v[12:15], v[112:115], v[204:207], v[12:15]
	v_mfma_f32_16x16x32_bf16 v[8:11], v[120:123], v[204:207], v[8:11]
	v_mfma_f32_16x16x32_bf16 v[60:63], v[116:119], v[132:135], v[60:63]
	v_mfma_f32_16x16x32_bf16 v[56:59], v[124:127], v[132:135], v[56:59]
	v_mfma_f32_16x16x32_bf16 v[44:47], v[116:119], v[166:169], v[44:47]
	v_mfma_f32_16x16x32_bf16 v[40:43], v[124:127], v[166:169], v[40:43]
	v_mfma_f32_16x16x32_bf16 v[28:31], v[116:119], v[200:203], v[28:31]
	v_mfma_f32_16x16x32_bf16 v[24:27], v[124:127], v[200:203], v[24:27]
	v_mfma_f32_16x16x32_bf16 v[12:15], v[116:119], v[208:211], v[12:15]
	v_mfma_f32_16x16x32_bf16 v[8:11], v[124:127], v[208:211], v[8:11]
	s_barrier
	s_add_u32 s28, s28, 0x100080
	s_addc_u32 s29, s29, 0
	s_add_i32 s21, s50, s54
	s_mov_b32 m0, s21
	s_nop 0
	global_load_lds_dwordx4 v176, s[28:29]
	s_add_i32 m0, s21, 0x2000
	s_nop 0
	global_load_lds_dwordx4 v152, s[28:29]
	s_waitcnt vmcnt(6)
	s_barrier
	v_mfma_f32_16x16x32_bf16 v[52:55], v[212:215], v[128:131], v[52:55]
	v_mfma_f32_16x16x32_bf16 v[48:51], v[232:235], v[128:131], v[48:51]
	v_mfma_f32_16x16x32_bf16 v[36:39], v[212:215], v[162:165], v[36:39]
	v_mfma_f32_16x16x32_bf16 v[32:35], v[232:235], v[162:165], v[32:35]
	v_mfma_f32_16x16x32_bf16 v[20:23], v[212:215], v[170:173], v[20:23]
	v_mfma_f32_16x16x32_bf16 v[16:19], v[232:235], v[170:173], v[16:19]
	v_mfma_f32_16x16x32_bf16 v[4:7], v[212:215], v[204:207], v[4:7]
	v_mfma_f32_16x16x32_bf16 v[0:3], v[232:235], v[204:207], v[0:3]
	v_mfma_f32_16x16x32_bf16 v[52:55], v[216:219], v[132:135], v[52:55]
	v_mfma_f32_16x16x32_bf16 v[48:51], v[236:239], v[132:135], v[48:51]
	v_mfma_f32_16x16x32_bf16 v[36:39], v[216:219], v[166:169], v[36:39]
	v_mfma_f32_16x16x32_bf16 v[32:35], v[236:239], v[166:169], v[32:35]
	v_mfma_f32_16x16x32_bf16 v[20:23], v[216:219], v[200:203], v[20:23]
	v_mfma_f32_16x16x32_bf16 v[16:19], v[236:239], v[200:203], v[16:19]
	v_mfma_f32_16x16x32_bf16 v[4:7], v[216:219], v[208:211], v[4:7]
	v_mfma_f32_16x16x32_bf16 v[0:3], v[236:239], v[208:211], v[0:3]
	s_add_i32 s20, s20, 2
	s_add_u32 s48, s48, 0x100
	s_addc_u32 s49, s49, 0
	s_add_u32 vcc_lo, vcc_lo, 0x100
	s_addc_u32 vcc_hi, vcc_hi, 0
	s_cmp_gt_u32 s20, 61
	s_barrier
	s_cbranch_scc0 .LBB0_100
	v_readlane_b32 s48, v252, 4
	v_readlane_b32 s49, v252, 5
	v_readlane_b32 s60, v252, 6
	v_readlane_b32 s61, v252, 7
	v_lshl_or_b32 v162, s34, 8, v198
	v_lshl_add_u32 v166, s2, 8, v174
	v_lshlrev_b32_e32 v163, 11, v166
	v_lshl_add_u32 v163, v162, 1, v163
	global_load_dwordx4 v[200:203], v163, s[68:69]
	global_load_dwordx4 v[204:207], v163, s[68:69] offset:256
	s_add_u32 s20, s68, 0x8000
	s_addc_u32 s21, s69, 0
	global_load_dwordx4 v[208:211], v163, s[20:21]
	global_load_dwordx4 v[212:215], v163, s[20:21] offset:256
	s_add_u32 s20, s68, 0x10000
	s_addc_u32 s21, s69, 0
	global_load_dwordx4 v[216:219], v163, s[20:21]
	global_load_dwordx4 v[232:235], v163, s[20:21] offset:256
	s_add_u32 s20, s68, 0x18000
	s_addc_u32 s21, s69, 0
	global_load_dwordx4 v[236:239], v163, s[20:21]
	global_load_dwordx4 v[240:243], v163, s[20:21] offset:256
	s_add_u32 s20, s68, 0x40000
	s_addc_u32 s21, s69, 0
	global_load_dwordx4 v[244:247], v163, s[20:21]
	global_load_dwordx4 v[248:251], v163, s[20:21] offset:256
	s_add_u32 s20, s68, 0x48000
	s_addc_u32 s21, s69, 0
	global_load_dwordx4 v[112:115], v163, s[20:21]
	global_load_dwordx4 v[116:119], v163, s[20:21] offset:256
	s_add_u32 s20, s68, 0x50000
	s_addc_u32 s21, s69, 0
	global_load_dwordx4 v[120:123], v163, s[20:21]
	global_load_dwordx4 v[124:127], v163, s[20:21] offset:256
	s_add_u32 s20, s68, 0x58000
	s_addc_u32 s21, s69, 0
	global_load_dwordx4 v[128:131], v163, s[20:21]
	global_load_dwordx4 v[132:135], v163, s[20:21] offset:256
	v_lshlrev_b32_e32 v164, 6, v166
	v_and_b32_e32 v165, 0x30, v225
	v_add_u32_e32 v165, v164, v165
	v_and_b32_e32 v171, 16, v225
	v_and_b32_e32 v172, 32, v225
	v_lshlrev_b32_e32 v171, 1, v171
	v_lshrrev_b32_e32 v172, 1, v172
	s_lshl_b32 s28, s34, 10
	s_lshl_b32 s29, s9, 7
	v_or_b32_e32 v171, v171, v172
	s_add_i32 s28, s28, s29
	v_add_u32_e32 v171, s28, v171
	v_lshl_add_u32 v167, v166, 12, v171
	v_lshlrev_b32_e32 v168, 2, v162
	v_xor_b32_e32 v169, 16, v225
	v_xor_b32_e32 v170, 32, v225
	v_lshlrev_b32_e32 v169, 2, v169
	v_lshlrev_b32_e32 v170, 2, v170
	s_cmpk_gt_u32 s92, 0xff
	s_cbranch_scc1 .Lf2e_nox
	s_barrier

.Lf2e_ready:
	s_add_u32 s72, s62, 0x2000
	s_addc_u32 s73, s63, 0
	global_load_dwordx4 v[200:203], v165, s[62:63] offset:0 sc1
	global_load_dwordx4 v[204:207], v165, s[62:63] offset:1024 sc1
	global_load_dwordx4 v[208:211], v165, s[62:63] offset:2048 sc1
	global_load_dwordx4 v[212:215], v165, s[62:63] offset:3072 sc1
	global_load_dwordx4 v[216:219], v165, s[72:73] offset:0 sc1
	global_load_dwordx4 v[232:235], v165, s[72:73] offset:1024 sc1
	global_load_dwordx4 v[236:239], v165, s[72:73] offset:2048 sc1
	global_load_dwordx4 v[240:243], v165, s[72:73] offset:3072 sc1
	s_waitcnt vmcnt(0)
	v_add_f32_e32 v200, v200, v201
	v_add_f32_e32 v202, v202, v203
	v_add_f32_e32 v204, v204, v205
	v_add_f32_e32 v206, v206, v207
	v_add_f32_e32 v208, v208, v209
	v_add_f32_e32 v210, v210, v211
	v_add_f32_e32 v212, v212, v213
	v_add_f32_e32 v214, v214, v215
	v_add_f32_e32 v216, v216, v217
	v_add_f32_e32 v218, v218, v219
	v_add_f32_e32 v232, v232, v233
	v_add_f32_e32 v234, v234, v235
	v_add_f32_e32 v236, v236, v237
	v_add_f32_e32 v238, v238, v239
	v_add_f32_e32 v240, v240, v241
	v_add_f32_e32 v242, v242, v243
	v_add_f32_e32 v200, v200, v202
	v_add_f32_e32 v204, v204, v206
	v_add_f32_e32 v208, v208, v210
	v_add_f32_e32 v212, v212, v214
	v_add_f32_e32 v216, v216, v218
	v_add_f32_e32 v232, v232, v234
	v_add_f32_e32 v236, v236, v238
	v_add_f32_e32 v240, v240, v242
	ds_bpermute_b32 v201, v169, v200
	ds_bpermute_b32 v205, v169, v204
	ds_bpermute_b32 v209, v169, v208
	ds_bpermute_b32 v213, v169, v212
	ds_bpermute_b32 v217, v169, v216
	ds_bpermute_b32 v233, v169, v232
	ds_bpermute_b32 v237, v169, v236
	ds_bpermute_b32 v241, v169, v240
	s_waitcnt lgkmcnt(0)
	v_add_f32_e32 v200, v200, v201
	v_add_f32_e32 v204, v204, v205
	v_add_f32_e32 v208, v208, v209
	v_add_f32_e32 v212, v212, v213
	v_add_f32_e32 v216, v216, v217
	v_add_f32_e32 v232, v232, v233
	v_add_f32_e32 v236, v236, v237
	v_add_f32_e32 v240, v240, v241
	ds_bpermute_b32 v201, v170, v200
	ds_bpermute_b32 v205, v170, v204
	ds_bpermute_b32 v209, v170, v208
	ds_bpermute_b32 v213, v170, v212
	ds_bpermute_b32 v217, v170, v216
	ds_bpermute_b32 v233, v170, v232
	ds_bpermute_b32 v237, v170, v236
	ds_bpermute_b32 v241, v170, v240
	s_waitcnt lgkmcnt(0)
	v_add_f32_e32 v200, v200, v201
	v_add_f32_e32 v204, v204, v205
	v_add_f32_e32 v208, v208, v209
	v_add_f32_e32 v212, v212, v213
	v_add_f32_e32 v216, v216, v217
	v_add_f32_e32 v232, v232, v233
	v_add_f32_e32 v236, v236, v237
	v_add_f32_e32 v240, v240, v241
	v_mul_f32_e32 v200, 0x3a800000, v200
	v_mul_f32_e32 v204, 0x3a800000, v204
	v_mul_f32_e32 v208, 0x3a800000, v208
	v_mul_f32_e32 v212, 0x3a800000, v212
	v_mul_f32_e32 v216, 0x3a800000, v216
	v_mul_f32_e32 v232, 0x3a800000, v232
	v_mul_f32_e32 v236, 0x3a800000, v236
	v_mul_f32_e32 v240, 0x3a800000, v240
	v_add_f32_e32 v200, 0x3727c5ac, v200
	v_add_f32_e32 v204, 0x3727c5ac, v204
	v_add_f32_e32 v208, 0x3727c5ac, v208
	v_add_f32_e32 v212, 0x3727c5ac, v212
	v_add_f32_e32 v216, 0x3727c5ac, v216
	v_add_f32_e32 v232, 0x3727c5ac, v232
	v_add_f32_e32 v236, 0x3727c5ac, v236
	v_add_f32_e32 v240, 0x3727c5ac, v240
	v_rsq_f32_e32 v200, v200
	v_rsq_f32_e32 v204, v204
	v_rsq_f32_e32 v208, v208
	v_rsq_f32_e32 v212, v212
	v_rsq_f32_e32 v216, v216
	v_rsq_f32_e32 v232, v232
	v_rsq_f32_e32 v236, v236
	v_rsq_f32_e32 v240, v240
	v_pk_mul_f32 v[148:149], v[200:201], v[148:149] op_sel_hi:[0,1]
	v_pk_mul_f32 v[150:151], v[200:201], v[150:151] op_sel_hi:[0,1]
	v_pk_mul_f32 v[148:149], v[120:121], v[148:149]
	v_pk_mul_f32 v[150:151], v[122:123], v[150:151]
	v_pk_mul_f32 v[144:145], v[200:201], v[144:145] op_sel_hi:[0,1]
	v_pk_mul_f32 v[146:147], v[200:201], v[146:147] op_sel_hi:[0,1]
	v_pk_mul_f32 v[144:145], v[124:125], v[144:145]
	v_pk_mul_f32 v[146:147], v[126:127], v[146:147]
	v_pk_mul_f32 v[140:141], v[200:201], v[140:141] op_sel_hi:[0,1]
	v_pk_mul_f32 v[142:143], v[200:201], v[142:143] op_sel_hi:[0,1]
	v_pk_mul_f32 v[140:141], v[128:129], v[140:141]
	v_pk_mul_f32 v[142:143], v[130:131], v[142:143]
	v_pk_mul_f32 v[136:137], v[200:201], v[136:137] op_sel_hi:[0,1]
	v_pk_mul_f32 v[138:139], v[200:201], v[138:139] op_sel_hi:[0,1]
	v_pk_mul_f32 v[136:137], v[132:133], v[136:137]
	v_pk_mul_f32 v[138:139], v[134:135], v[138:139]
	v_permlane32_swap_b32_e32 v148, v144
	v_permlane32_swap_b32_e32 v149, v145
	v_permlane32_swap_b32_e32 v150, v146
	v_permlane32_swap_b32_e32 v151, v147
	global_store_dwordx4 v167, v[148:151], s[60:61]
	global_store_dwordx4 v167, v[144:147], s[60:61] offset:64
	s_nop 0
	v_permlane32_swap_b32_e32 v140, v136
	v_permlane32_swap_b32_e32 v141, v137
	v_permlane32_swap_b32_e32 v142, v138
	v_permlane32_swap_b32_e32 v143, v139
	global_store_dwordx4 v167, v[140:143], s[60:61] offset:512
	global_store_dwordx4 v167, v[136:139], s[60:61] offset:576
	s_add_u32 s28, s60, 0x10000
	s_addc_u32 s29, s61, 0
	v_pk_mul_f32 v[108:109], v[204:205], v[108:109] op_sel_hi:[0,1]
	v_pk_mul_f32 v[110:111], v[204:205], v[110:111] op_sel_hi:[0,1]
	v_pk_mul_f32 v[108:109], v[120:121], v[108:109]
	v_pk_mul_f32 v[110:111], v[122:123], v[110:111]
	v_pk_mul_f32 v[104:105], v[204:205], v[104:105] op_sel_hi:[0,1]
	v_pk_mul_f32 v[106:107], v[204:205], v[106:107] op_sel_hi:[0,1]
	v_pk_mul_f32 v[104:105], v[124:125], v[104:105]
	v_pk_mul_f32 v[106:107], v[126:127], v[106:107]
	v_pk_mul_f32 v[100:101], v[204:205], v[100:101] op_sel_hi:[0,1]
	v_pk_mul_f32 v[102:103], v[204:205], v[102:103] op_sel_hi:[0,1]
	v_pk_mul_f32 v[100:101], v[128:129], v[100:101]
	v_pk_mul_f32 v[102:103], v[130:131], v[102:103]
	v_pk_mul_f32 v[96:97], v[204:205], v[96:97] op_sel_hi:[0,1]
	v_pk_mul_f32 v[98:99], v[204:205], v[98:99] op_sel_hi:[0,1]
	v_pk_mul_f32 v[96:97], v[132:133], v[96:97]
	v_pk_mul_f32 v[98:99], v[134:135], v[98:99]
	v_permlane32_swap_b32_e32 v108, v104
	v_permlane32_swap_b32_e32 v109, v105
	v_permlane32_swap_b32_e32 v110, v106
	v_permlane32_swap_b32_e32 v111, v107
	global_store_dwordx4 v167, v[108:111], s[28:29]
	global_store_dwordx4 v167, v[104:107], s[28:29] offset:64
	s_nop 0
	v_permlane32_swap_b32_e32 v100, v96
	v_permlane32_swap_b32_e32 v101, v97
	v_permlane32_swap_b32_e32 v102, v98
	v_permlane32_swap_b32_e32 v103, v99
	global_store_dwordx4 v167, v[100:103], s[28:29] offset:512
	global_store_dwordx4 v167, v[96:99], s[28:29] offset:576
	s_add_u32 s28, s60, 0x20000
	s_addc_u32 s29, s61, 0
	v_pk_mul_f32 v[92:93], v[208:209], v[92:93] op_sel_hi:[0,1]
	v_pk_mul_f32 v[94:95], v[208:209], v[94:95] op_sel_hi:[0,1]
	v_pk_mul_f32 v[92:93], v[120:121], v[92:93]
	v_pk_mul_f32 v[94:95], v[122:123], v[94:95]
	v_pk_mul_f32 v[88:89], v[208:209], v[88:89] op_sel_hi:[0,1]
	v_pk_mul_f32 v[90:91], v[208:209], v[90:91] op_sel_hi:[0,1]
	v_pk_mul_f32 v[88:89], v[124:125], v[88:89]
	v_pk_mul_f32 v[90:91], v[126:127], v[90:91]
	v_pk_mul_f32 v[84:85], v[208:209], v[84:85] op_sel_hi:[0,1]
	v_pk_mul_f32 v[86:87], v[208:209], v[86:87] op_sel_hi:[0,1]
	v_pk_mul_f32 v[84:85], v[128:129], v[84:85]
	v_pk_mul_f32 v[86:87], v[130:131], v[86:87]
	v_pk_mul_f32 v[80:81], v[208:209], v[80:81] op_sel_hi:[0,1]
	v_pk_mul_f32 v[82:83], v[208:209], v[82:83] op_sel_hi:[0,1]
	v_pk_mul_f32 v[80:81], v[132:133], v[80:81]
	v_pk_mul_f32 v[82:83], v[134:135], v[82:83]
	v_permlane32_swap_b32_e32 v92, v88
	v_permlane32_swap_b32_e32 v93, v89
	v_permlane32_swap_b32_e32 v94, v90
	v_permlane32_swap_b32_e32 v95, v91
	global_store_dwordx4 v167, v[92:95], s[28:29]
	global_store_dwordx4 v167, v[88:91], s[28:29] offset:64
	s_nop 0
	v_permlane32_swap_b32_e32 v84, v80
	v_permlane32_swap_b32_e32 v85, v81
	v_permlane32_swap_b32_e32 v86, v82
	v_permlane32_swap_b32_e32 v87, v83
	global_store_dwordx4 v167, v[84:87], s[28:29] offset:512
	global_store_dwordx4 v167, v[80:83], s[28:29] offset:576
	s_add_u32 s28, s60, 0x30000
	s_addc_u32 s29, s61, 0
	v_pk_mul_f32 v[76:77], v[212:213], v[76:77] op_sel_hi:[0,1]
	v_pk_mul_f32 v[78:79], v[212:213], v[78:79] op_sel_hi:[0,1]
	v_pk_mul_f32 v[76:77], v[120:121], v[76:77]
	v_pk_mul_f32 v[78:79], v[122:123], v[78:79]
	v_pk_mul_f32 v[72:73], v[212:213], v[72:73] op_sel_hi:[0,1]
	v_pk_mul_f32 v[74:75], v[212:213], v[74:75] op_sel_hi:[0,1]
	v_pk_mul_f32 v[72:73], v[124:125], v[72:73]
	v_pk_mul_f32 v[74:75], v[126:127], v[74:75]
	v_pk_mul_f32 v[68:69], v[212:213], v[68:69] op_sel_hi:[0,1]
	v_pk_mul_f32 v[70:71], v[212:213], v[70:71] op_sel_hi:[0,1]
	v_pk_mul_f32 v[68:69], v[128:129], v[68:69]
	v_pk_mul_f32 v[70:71], v[130:131], v[70:71]
	v_pk_mul_f32 v[64:65], v[212:213], v[64:65] op_sel_hi:[0,1]
	v_pk_mul_f32 v[66:67], v[212:213], v[66:67] op_sel_hi:[0,1]
	v_pk_mul_f32 v[64:65], v[132:133], v[64:65]
	v_pk_mul_f32 v[66:67], v[134:135], v[66:67]
	v_permlane32_swap_b32_e32 v76, v72
	v_permlane32_swap_b32_e32 v77, v73
	v_permlane32_swap_b32_e32 v78, v74
	v_permlane32_swap_b32_e32 v79, v75
	global_store_dwordx4 v167, v[76:79], s[28:29]
	global_store_dwordx4 v167, v[72:75], s[28:29] offset:64
	s_nop 0
	v_permlane32_swap_b32_e32 v68, v64
	v_permlane32_swap_b32_e32 v69, v65
	v_permlane32_swap_b32_e32 v70, v66
	v_permlane32_swap_b32_e32 v71, v67
	global_store_dwordx4 v167, v[68:71], s[28:29] offset:512
	global_store_dwordx4 v167, v[64:67], s[28:29] offset:576
	s_add_u32 s28, s60, 0x80000
	s_addc_u32 s29, s61, 0
	v_pk_mul_f32 v[60:61], v[216:217], v[60:61] op_sel_hi:[0,1]
	v_pk_mul_f32 v[62:63], v[216:217], v[62:63] op_sel_hi:[0,1]
	v_pk_mul_f32 v[60:61], v[120:121], v[60:61]
	v_pk_mul_f32 v[62:63], v[122:123], v[62:63]
	v_pk_mul_f32 v[56:57], v[216:217], v[56:57] op_sel_hi:[0,1]
	v_pk_mul_f32 v[58:59], v[216:217], v[58:59] op_sel_hi:[0,1]
	v_pk_mul_f32 v[56:57], v[124:125], v[56:57]
	v_pk_mul_f32 v[58:59], v[126:127], v[58:59]
	v_pk_mul_f32 v[52:53], v[216:217], v[52:53] op_sel_hi:[0,1]
	v_pk_mul_f32 v[54:55], v[216:217], v[54:55] op_sel_hi:[0,1]
	v_pk_mul_f32 v[52:53], v[128:129], v[52:53]
	v_pk_mul_f32 v[54:55], v[130:131], v[54:55]
	v_pk_mul_f32 v[48:49], v[216:217], v[48:49] op_sel_hi:[0,1]
	v_pk_mul_f32 v[50:51], v[216:217], v[50:51] op_sel_hi:[0,1]
	v_pk_mul_f32 v[48:49], v[132:133], v[48:49]
	v_pk_mul_f32 v[50:51], v[134:135], v[50:51]
	v_permlane32_swap_b32_e32 v60, v56
	v_permlane32_swap_b32_e32 v61, v57
	v_permlane32_swap_b32_e32 v62, v58
	v_permlane32_swap_b32_e32 v63, v59
	global_store_dwordx4 v167, v[60:63], s[28:29]
	global_store_dwordx4 v167, v[56:59], s[28:29] offset:64
	s_nop 0
	v_permlane32_swap_b32_e32 v52, v48
	v_permlane32_swap_b32_e32 v53, v49
	v_permlane32_swap_b32_e32 v54, v50
	v_permlane32_swap_b32_e32 v55, v51
	global_store_dwordx4 v167, v[52:55], s[28:29] offset:512
	global_store_dwordx4 v167, v[48:51], s[28:29] offset:576
	s_add_u32 s28, s60, 0x90000
	s_addc_u32 s29, s61, 0
	v_pk_mul_f32 v[44:45], v[232:233], v[44:45] op_sel_hi:[0,1]
	v_pk_mul_f32 v[46:47], v[232:233], v[46:47] op_sel_hi:[0,1]
	v_pk_mul_f32 v[44:45], v[120:121], v[44:45]
	v_pk_mul_f32 v[46:47], v[122:123], v[46:47]
	v_pk_mul_f32 v[40:41], v[232:233], v[40:41] op_sel_hi:[0,1]
	v_pk_mul_f32 v[42:43], v[232:233], v[42:43] op_sel_hi:[0,1]
	v_pk_mul_f32 v[40:41], v[124:125], v[40:41]
	v_pk_mul_f32 v[42:43], v[126:127], v[42:43]
	v_pk_mul_f32 v[36:37], v[232:233], v[36:37] op_sel_hi:[0,1]
	v_pk_mul_f32 v[38:39], v[232:233], v[38:39] op_sel_hi:[0,1]
	v_pk_mul_f32 v[36:37], v[128:129], v[36:37]
	v_pk_mul_f32 v[38:39], v[130:131], v[38:39]
	v_pk_mul_f32 v[32:33], v[232:233], v[32:33] op_sel_hi:[0,1]
	v_pk_mul_f32 v[34:35], v[232:233], v[34:35] op_sel_hi:[0,1]
	v_pk_mul_f32 v[32:33], v[132:133], v[32:33]
	v_pk_mul_f32 v[34:35], v[134:135], v[34:35]
	v_permlane32_swap_b32_e32 v44, v40
	v_permlane32_swap_b32_e32 v45, v41
	v_permlane32_swap_b32_e32 v46, v42
	v_permlane32_swap_b32_e32 v47, v43
	global_store_dwordx4 v167, v[44:47], s[28:29]
	global_store_dwordx4 v167, v[40:43], s[28:29] offset:64
	s_nop 0
	v_permlane32_swap_b32_e32 v36, v32
	v_permlane32_swap_b32_e32 v37, v33
	v_permlane32_swap_b32_e32 v38, v34
	v_permlane32_swap_b32_e32 v39, v35
	global_store_dwordx4 v167, v[36:39], s[28:29] offset:512
	global_store_dwordx4 v167, v[32:35], s[28:29] offset:576
	s_add_u32 s28, s60, 0xa0000
	s_addc_u32 s29, s61, 0
	v_pk_mul_f32 v[28:29], v[236:237], v[28:29] op_sel_hi:[0,1]
	v_pk_mul_f32 v[30:31], v[236:237], v[30:31] op_sel_hi:[0,1]
	v_pk_mul_f32 v[28:29], v[120:121], v[28:29]
	v_pk_mul_f32 v[30:31], v[122:123], v[30:31]
	v_pk_mul_f32 v[24:25], v[236:237], v[24:25] op_sel_hi:[0,1]
	v_pk_mul_f32 v[26:27], v[236:237], v[26:27] op_sel_hi:[0,1]
	v_pk_mul_f32 v[24:25], v[124:125], v[24:25]
	v_pk_mul_f32 v[26:27], v[126:127], v[26:27]
	v_pk_mul_f32 v[20:21], v[236:237], v[20:21] op_sel_hi:[0,1]
	v_pk_mul_f32 v[22:23], v[236:237], v[22:23] op_sel_hi:[0,1]
	v_pk_mul_f32 v[20:21], v[128:129], v[20:21]
	v_pk_mul_f32 v[22:23], v[130:131], v[22:23]
	v_pk_mul_f32 v[16:17], v[236:237], v[16:17] op_sel_hi:[0,1]
	v_pk_mul_f32 v[18:19], v[236:237], v[18:19] op_sel_hi:[0,1]
	v_pk_mul_f32 v[16:17], v[132:133], v[16:17]
	v_pk_mul_f32 v[18:19], v[134:135], v[18:19]
	v_permlane32_swap_b32_e32 v28, v24
	v_permlane32_swap_b32_e32 v29, v25
	v_permlane32_swap_b32_e32 v30, v26
	v_permlane32_swap_b32_e32 v31, v27
	global_store_dwordx4 v167, v[28:31], s[28:29]
	global_store_dwordx4 v167, v[24:27], s[28:29] offset:64
	s_nop 0
	v_permlane32_swap_b32_e32 v20, v16
	v_permlane32_swap_b32_e32 v21, v17
	v_permlane32_swap_b32_e32 v22, v18
	v_permlane32_swap_b32_e32 v23, v19
	global_store_dwordx4 v167, v[20:23], s[28:29] offset:512
	global_store_dwordx4 v167, v[16:19], s[28:29] offset:576
	s_add_u32 s28, s60, 0xb0000
	s_addc_u32 s29, s61, 0
	v_pk_mul_f32 v[12:13], v[240:241], v[12:13] op_sel_hi:[0,1]
	v_pk_mul_f32 v[14:15], v[240:241], v[14:15] op_sel_hi:[0,1]
	v_pk_mul_f32 v[12:13], v[120:121], v[12:13]
	v_pk_mul_f32 v[14:15], v[122:123], v[14:15]
	v_pk_mul_f32 v[8:9], v[240:241], v[8:9] op_sel_hi:[0,1]
	v_pk_mul_f32 v[10:11], v[240:241], v[10:11] op_sel_hi:[0,1]
	v_pk_mul_f32 v[8:9], v[124:125], v[8:9]
	v_pk_mul_f32 v[10:11], v[126:127], v[10:11]
	v_pk_mul_f32 v[4:5], v[240:241], v[4:5] op_sel_hi:[0,1]
	v_pk_mul_f32 v[6:7], v[240:241], v[6:7] op_sel_hi:[0,1]
	v_pk_mul_f32 v[4:5], v[128:129], v[4:5]
	v_pk_mul_f32 v[6:7], v[130:131], v[6:7]
	v_pk_mul_f32 v[0:1], v[240:241], v[0:1] op_sel_hi:[0,1]
	v_pk_mul_f32 v[2:3], v[240:241], v[2:3] op_sel_hi:[0,1]
	v_pk_mul_f32 v[0:1], v[132:133], v[0:1]
	v_pk_mul_f32 v[2:3], v[134:135], v[2:3]
	v_permlane32_swap_b32_e32 v12, v8
	v_permlane32_swap_b32_e32 v13, v9
	v_permlane32_swap_b32_e32 v14, v10
	v_permlane32_swap_b32_e32 v15, v11
	global_store_dwordx4 v167, v[12:15], s[28:29]
	global_store_dwordx4 v167, v[8:11], s[28:29] offset:64
	s_nop 0
	v_permlane32_swap_b32_e32 v4, v0
	v_permlane32_swap_b32_e32 v5, v1
	v_permlane32_swap_b32_e32 v6, v2
	v_permlane32_swap_b32_e32 v7, v3
	global_store_dwordx4 v167, v[4:7], s[28:29] offset:512
	global_store_dwordx4 v167, v[0:3], s[28:29] offset:576
	s_mov_b64 s[28:29], -1
	s_branch .LBB0_92
